# P0(b) MLP on f32 matrix cores + 60-byte skip pad so later code keeps the same 64B placement as before
# baseline (speedup 1.0000x reference)
.LBB0_32:
	s_or_b64 exec, exec, s[0:1]
	s_movk_i32 s0, 0x600
	v_cmp_gt_i32_e32 vcc, s0, v66
	s_waitcnt lgkmcnt(0)
	s_barrier
	s_and_saveexec_b64 s[8:9], vcc
	s_cbranch_execz .LBB0_39
	v_and_b32_e32 v71, 15, v64
	v_lshrrev_b32_e32 v72, 4, v64
	v_readfirstlane_b32 s24, v66
	v_lshlrev_b32_e32 v67, 8, v72
	v_lshl_add_u32 v67, v71, 2, v67
	v_lshlrev_b32_e32 v70, 4, v72
	ds_read_b128 v[20:23], v70 offset:41984
	ds_read_b128 v[24:27], v70 offset:42048
	ds_read_b128 v[28:31], v70 offset:42112
	ds_read_b128 v[32:35], v70 offset:42176
	v_mul_u32_u24_e32 v73, 0x110, v71
	v_mul_u32_u24_e32 v74, 0x1100, v200
	v_add_u32_e32 v74, 0xa800, v74
	v_add_u32_e32 v73, v73, v74
	v_lshl_add_u32 v68, v72, 2, v73
	v_lshl_add_u32 v69, v72, 4, v73
	s_lshl_b32 s25, s24, 4
	s_mov_b32 s30, 0x38800000
	s_mov_b32 s31, 0x39000000
	s_mov_b32 s0, 0x467ffc00
	s_mov_b32 s1, 0x45fff800
	s_cmp_lt_u32 s25, 0x4000
	s_cselect_b32 s30, s30, s31
	s_cselect_b32 s31, s0, s1
	s_cselect_b32 s26, 0, 0x4000
	s_sub_u32 s27, s25, s26
	v_add_u32_e32 v75, s27, v71
	v_cvt_f32_i32_e32 v75, v75
	v_mov_b32_e32 v76, s31
	v_div_scale_f32 v82, s[36:37], v76, v76, v75
	v_rcp_f32_e32 v83, v82
	v_div_scale_f32 v84, vcc, v75, v76, v75
	v_fma_f32 v85, -v82, v83, 1.0
	v_fmac_f32_e32 v83, v85, v83
	v_mul_f32_e32 v85, v84, v83
	v_fma_f32 v86, -v82, v85, v84
	v_fmac_f32_e32 v85, v86, v83
	v_fma_f32 v82, -v82, v85, v84
	v_div_fmas_f32 v82, v82, v83, v85
	v_div_fixup_f32 v77, v82, v76, v75
	v_cmp_eq_u32_e64 s[0:1], 0, v72
	v_add_u32_e32 v78, -1, v72
	v_and_b32_e32 v78, 15, v78
	v_cvt_f32_ubyte0_e32 v78, v78
	v_mov_b32_e32 v79, 0x38d1b717
	v_fmac_f32_e32 v79, 0x3f7fff90, v78
	v_mul_f32_e32 v79, v79, v75
	v_mul_f32_e32 v79, s30, v79
	v_cos_f32_e32 v80, v79
	v_sin_f32_e64 v81, -v79
	v_add_u32_e32 v78, 3, v72
	v_and_b32_e32 v78, 15, v78
	v_cvt_f32_ubyte0_e32 v78, v78
	v_mov_b32_e32 v79, 0x38d1b717
	v_fmac_f32_e32 v79, 0x3f7fff90, v78
	v_mul_f32_e32 v79, v79, v75
	v_mul_f32_e32 v79, s30, v79
	v_cos_f32_e32 v37, v79
	v_sin_f32_e64 v41, -v79
	v_add_u32_e32 v78, 7, v72
	v_and_b32_e32 v78, 15, v78
	v_cvt_f32_ubyte0_e32 v78, v78
	v_mov_b32_e32 v79, 0x38d1b717
	v_fmac_f32_e32 v79, 0x3f7fff90, v78
	v_mul_f32_e32 v79, v79, v75
	v_mul_f32_e32 v79, s30, v79
	v_cos_f32_e32 v38, v79
	v_sin_f32_e64 v42, -v79
	v_add_u32_e32 v78, 11, v72
	v_and_b32_e32 v78, 15, v78
	v_cvt_f32_ubyte0_e32 v78, v78
	v_mov_b32_e32 v79, 0x38d1b717
	v_fmac_f32_e32 v79, 0x3f7fff90, v78
	v_mul_f32_e32 v79, v79, v75
	v_mul_f32_e32 v79, s30, v79
	v_cos_f32_e32 v39, v79
	v_sin_f32_e64 v43, -v79
	s_nop 0
	v_cndmask_b32_e64 v36, v80, v77, s[0:1]
	v_cndmask_b32_e64 v40, v81, v80, s[0:1]
	v_cndmask_b32_e64 v44, 0, v81, s[0:1]
	s_waitcnt lgkmcnt(0)
	v_mul_f32_e32 v20, 0.15915494, v20
	v_mul_f32_e32 v21, 0.15915494, v21
	v_mul_f32_e32 v22, 0.15915494, v22
	v_mul_f32_e32 v23, 0.15915494, v23
	v_mul_f32_e32 v24, 0.15915494, v24
	v_mul_f32_e32 v25, 0.15915494, v25
	v_mul_f32_e32 v26, 0.15915494, v26
	v_mul_f32_e32 v27, 0.15915494, v27
	v_mul_f32_e32 v28, 0.15915494, v28
	v_mul_f32_e32 v29, 0.15915494, v29
	v_mul_f32_e32 v30, 0.15915494, v30
	v_mul_f32_e32 v31, 0.15915494, v31
	v_mul_f32_e32 v32, 0.15915494, v32
	v_mul_f32_e32 v33, 0.15915494, v33
	v_mul_f32_e32 v34, 0.15915494, v34
	v_mul_f32_e32 v35, 0.15915494, v35
	s_add_u32 s26, s56, 0x1e420000
	s_addc_u32 s27, s57, 0
	s_lshl_b32 s4, s24, 11
	s_add_u32 s26, s26, s4
	s_addc_u32 s27, s27, 0
	v_lshlrev_b32_e32 v92, 7, v71
	v_lshl_add_u32 v92, v72, 3, v92
	s_mov_b32 s30, 0x7fff
	s_mov_b32 s31, 0x7060302
	ds_read_b128 v[4:7], v70 offset:41216
	ds_read_b128 v[8:11], v70 offset:41280
	ds_read_b128 v[12:15], v70 offset:41344
	ds_read_b128 v[16:19], v70 offset:41408
	ds_read_b32 v45, v67 offset:0
	ds_read_b32 v46, v67 offset:64
	ds_read_b32 v47, v67 offset:128
	ds_read_b32 v48, v67 offset:192
	ds_read_b32 v50, v67 offset:1024
	ds_read_b32 v51, v67 offset:1088
	ds_read_b32 v52, v67 offset:1152
	ds_read_b32 v53, v67 offset:1216
	s_waitcnt lgkmcnt(4)
	v_mfma_f32_16x16x4_f32 v[4:7], v45, v36, v[4:7]
	ds_read_b32 v55, v67 offset:2048
	ds_read_b32 v56, v67 offset:2112
	ds_read_b32 v57, v67 offset:2176
	ds_read_b32 v58, v67 offset:2240
	v_mfma_f32_16x16x4_f32 v[8:11], v46, v36, v[8:11]
	v_mfma_f32_16x16x4_f32 v[12:15], v47, v36, v[12:15]
	v_mfma_f32_16x16x4_f32 v[16:19], v48, v36, v[16:19]
	s_waitcnt lgkmcnt(4)
	v_mfma_f32_16x16x4_f32 v[4:7], v50, v37, v[4:7]
	ds_read_b32 v45, v67 offset:3072
	ds_read_b32 v46, v67 offset:3136
	ds_read_b32 v47, v67 offset:3200
	ds_read_b32 v48, v67 offset:3264
	v_mfma_f32_16x16x4_f32 v[8:11], v51, v37, v[8:11]
	v_mfma_f32_16x16x4_f32 v[12:15], v52, v37, v[12:15]
	v_mfma_f32_16x16x4_f32 v[16:19], v53, v37, v[16:19]
	s_waitcnt lgkmcnt(4)
	v_mfma_f32_16x16x4_f32 v[4:7], v55, v38, v[4:7]
	ds_read_b32 v50, v67 offset:4096
	ds_read_b32 v51, v67 offset:4160
	ds_read_b32 v52, v67 offset:4224
	ds_read_b32 v53, v67 offset:4288
	v_mfma_f32_16x16x4_f32 v[8:11], v56, v38, v[8:11]
	v_mfma_f32_16x16x4_f32 v[12:15], v57, v38, v[12:15]
	v_mfma_f32_16x16x4_f32 v[16:19], v58, v38, v[16:19]
	s_waitcnt lgkmcnt(4)
	v_mfma_f32_16x16x4_f32 v[4:7], v45, v39, v[4:7]
	ds_read_b32 v55, v67 offset:5120
	ds_read_b32 v56, v67 offset:5184
	ds_read_b32 v57, v67 offset:5248
	ds_read_b32 v58, v67 offset:5312
	v_mfma_f32_16x16x4_f32 v[8:11], v46, v39, v[8:11]
	v_mfma_f32_16x16x4_f32 v[12:15], v47, v39, v[12:15]
	v_mfma_f32_16x16x4_f32 v[16:19], v48, v39, v[16:19]
	s_waitcnt lgkmcnt(4)
	v_mfma_f32_16x16x4_f32 v[4:7], v50, v40, v[4:7]
	ds_read_b32 v45, v67 offset:6144
	ds_read_b32 v46, v67 offset:6208
	ds_read_b32 v47, v67 offset:6272
	ds_read_b32 v48, v67 offset:6336
	v_mfma_f32_16x16x4_f32 v[8:11], v51, v40, v[8:11]
	v_mfma_f32_16x16x4_f32 v[12:15], v52, v40, v[12:15]
	v_mfma_f32_16x16x4_f32 v[16:19], v53, v40, v[16:19]
	s_waitcnt lgkmcnt(4)
	v_mfma_f32_16x16x4_f32 v[4:7], v55, v41, v[4:7]
	ds_read_b32 v50, v67 offset:7168
	ds_read_b32 v51, v67 offset:7232
	ds_read_b32 v52, v67 offset:7296
	ds_read_b32 v53, v67 offset:7360
	v_mfma_f32_16x16x4_f32 v[8:11], v56, v41, v[8:11]
	v_mfma_f32_16x16x4_f32 v[12:15], v57, v41, v[12:15]
	v_mfma_f32_16x16x4_f32 v[16:19], v58, v41, v[16:19]
	s_waitcnt lgkmcnt(4)
	v_mfma_f32_16x16x4_f32 v[4:7], v45, v42, v[4:7]
	ds_read_b32 v55, v67 offset:8192
	ds_read_b32 v56, v67 offset:8256
	ds_read_b32 v57, v67 offset:8320
	ds_read_b32 v58, v67 offset:8384
	v_mfma_f32_16x16x4_f32 v[8:11], v46, v42, v[8:11]
	v_mfma_f32_16x16x4_f32 v[12:15], v47, v42, v[12:15]
	v_mfma_f32_16x16x4_f32 v[16:19], v48, v42, v[16:19]
	s_waitcnt lgkmcnt(4)
	v_mfma_f32_16x16x4_f32 v[4:7], v50, v43, v[4:7]
	v_mfma_f32_16x16x4_f32 v[8:11], v51, v43, v[8:11]
	v_mfma_f32_16x16x4_f32 v[12:15], v52, v43, v[12:15]
	v_mfma_f32_16x16x4_f32 v[16:19], v53, v43, v[16:19]
	s_waitcnt lgkmcnt(0)
	v_mfma_f32_16x16x4_f32 v[4:7], v55, v44, v[4:7]
	v_mfma_f32_16x16x4_f32 v[8:11], v56, v44, v[8:11]
	v_mfma_f32_16x16x4_f32 v[12:15], v57, v44, v[12:15]
	v_mfma_f32_16x16x4_f32 v[16:19], v58, v44, v[16:19]
	s_nop 7
	s_nop 3
	v_mul_f32_e32 v4, v20, v4
	v_mul_f32_e32 v5, v21, v5
	v_mul_f32_e32 v6, v22, v6
	v_mul_f32_e32 v7, v23, v7
	v_mul_f32_e32 v8, v24, v8
	v_mul_f32_e32 v9, v25, v9
	v_mul_f32_e32 v10, v26, v10
	v_mul_f32_e32 v11, v27, v11
	v_mul_f32_e32 v12, v28, v12
	v_mul_f32_e32 v13, v29, v13
	v_mul_f32_e32 v14, v30, v14
	v_mul_f32_e32 v15, v31, v15
	v_mul_f32_e32 v16, v32, v16
	v_mul_f32_e32 v17, v33, v17
	v_mul_f32_e32 v18, v34, v18
	v_mul_f32_e32 v19, v35, v19
	v_sin_f32_e32 v4, v4
	v_sin_f32_e32 v5, v5
	v_sin_f32_e32 v6, v6
	v_sin_f32_e32 v7, v7
	v_sin_f32_e32 v8, v8
	v_sin_f32_e32 v9, v9
	v_sin_f32_e32 v10, v10
	v_sin_f32_e32 v11, v11
	v_sin_f32_e32 v12, v12
	v_sin_f32_e32 v13, v13
	v_sin_f32_e32 v14, v14
	v_sin_f32_e32 v15, v15
	v_sin_f32_e32 v16, v16
	v_sin_f32_e32 v17, v17
	v_sin_f32_e32 v18, v18
	v_sin_f32_e32 v19, v19
	s_nop 1
	ds_write_b128 v69, v[4:7] offset:0
	ds_write_b128 v69, v[8:11] offset:64
	ds_write_b128 v69, v[12:15] offset:128
	ds_write_b128 v69, v[16:19] offset:192
	s_waitcnt lgkmcnt(0)
	ds_read_b128 v[100:103], v70 offset:41472
	ds_read_b128 v[104:107], v70 offset:41536
	ds_read_b128 v[108:111], v70 offset:41600
	ds_read_b128 v[112:115], v70 offset:41664
	ds_read_b32 v49, v68 offset:0
	ds_read_b32 v45, v67 offset:8448
	ds_read_b32 v46, v67 offset:8512
	ds_read_b32 v47, v67 offset:8576
	ds_read_b32 v48, v67 offset:8640
	ds_read_b32 v54, v68 offset:16
	ds_read_b32 v50, v67 offset:9472
	ds_read_b32 v51, v67 offset:9536
	ds_read_b32 v52, v67 offset:9600
	ds_read_b32 v53, v67 offset:9664
	s_waitcnt lgkmcnt(5)
	v_mfma_f32_16x16x4_f32 v[100:103], v45, v49, v[100:103]
	ds_read_b32 v59, v68 offset:32
	ds_read_b32 v55, v67 offset:10496
	ds_read_b32 v56, v67 offset:10560
	ds_read_b32 v57, v67 offset:10624
	ds_read_b32 v58, v67 offset:10688
	v_mfma_f32_16x16x4_f32 v[104:107], v46, v49, v[104:107]
	v_mfma_f32_16x16x4_f32 v[108:111], v47, v49, v[108:111]
	v_mfma_f32_16x16x4_f32 v[112:115], v48, v49, v[112:115]
	s_waitcnt lgkmcnt(5)
	v_mfma_f32_16x16x4_f32 v[100:103], v50, v54, v[100:103]
	ds_read_b32 v49, v68 offset:48
	ds_read_b32 v45, v67 offset:11520
	ds_read_b32 v46, v67 offset:11584
	ds_read_b32 v47, v67 offset:11648
	ds_read_b32 v48, v67 offset:11712
	v_mfma_f32_16x16x4_f32 v[104:107], v51, v54, v[104:107]
	v_mfma_f32_16x16x4_f32 v[108:111], v52, v54, v[108:111]
	v_mfma_f32_16x16x4_f32 v[112:115], v53, v54, v[112:115]
	s_waitcnt lgkmcnt(5)
	v_mfma_f32_16x16x4_f32 v[100:103], v55, v59, v[100:103]
	ds_read_b32 v54, v68 offset:64
	ds_read_b32 v50, v67 offset:12544
	ds_read_b32 v51, v67 offset:12608
	ds_read_b32 v52, v67 offset:12672
	ds_read_b32 v53, v67 offset:12736
	v_mfma_f32_16x16x4_f32 v[104:107], v56, v59, v[104:107]
	v_mfma_f32_16x16x4_f32 v[108:111], v57, v59, v[108:111]
	v_mfma_f32_16x16x4_f32 v[112:115], v58, v59, v[112:115]
	s_waitcnt lgkmcnt(5)
	v_mfma_f32_16x16x4_f32 v[100:103], v45, v49, v[100:103]
	ds_read_b32 v59, v68 offset:80
	ds_read_b32 v55, v67 offset:13568
	ds_read_b32 v56, v67 offset:13632
	ds_read_b32 v57, v67 offset:13696
	ds_read_b32 v58, v67 offset:13760
	v_mfma_f32_16x16x4_f32 v[104:107], v46, v49, v[104:107]
	v_mfma_f32_16x16x4_f32 v[108:111], v47, v49, v[108:111]
	v_mfma_f32_16x16x4_f32 v[112:115], v48, v49, v[112:115]
	s_waitcnt lgkmcnt(5)
	v_mfma_f32_16x16x4_f32 v[100:103], v50, v54, v[100:103]
	ds_read_b32 v49, v68 offset:96
	ds_read_b32 v45, v67 offset:14592
	ds_read_b32 v46, v67 offset:14656
	ds_read_b32 v47, v67 offset:14720
	ds_read_b32 v48, v67 offset:14784
	v_mfma_f32_16x16x4_f32 v[104:107], v51, v54, v[104:107]
	v_mfma_f32_16x16x4_f32 v[108:111], v52, v54, v[108:111]
	v_mfma_f32_16x16x4_f32 v[112:115], v53, v54, v[112:115]
	s_waitcnt lgkmcnt(5)
	v_mfma_f32_16x16x4_f32 v[100:103], v55, v59, v[100:103]
	ds_read_b32 v54, v68 offset:112
	ds_read_b32 v50, v67 offset:15616
	ds_read_b32 v51, v67 offset:15680
	ds_read_b32 v52, v67 offset:15744
	ds_read_b32 v53, v67 offset:15808
	v_mfma_f32_16x16x4_f32 v[104:107], v56, v59, v[104:107]
	v_mfma_f32_16x16x4_f32 v[108:111], v57, v59, v[108:111]
	v_mfma_f32_16x16x4_f32 v[112:115], v58, v59, v[112:115]
	s_waitcnt lgkmcnt(5)
	v_mfma_f32_16x16x4_f32 v[100:103], v45, v49, v[100:103]
	ds_read_b32 v59, v68 offset:128
	ds_read_b32 v55, v67 offset:16640
	ds_read_b32 v56, v67 offset:16704
	ds_read_b32 v57, v67 offset:16768
	ds_read_b32 v58, v67 offset:16832
	v_mfma_f32_16x16x4_f32 v[104:107], v46, v49, v[104:107]
	v_mfma_f32_16x16x4_f32 v[108:111], v47, v49, v[108:111]
	v_mfma_f32_16x16x4_f32 v[112:115], v48, v49, v[112:115]
	s_waitcnt lgkmcnt(5)
	v_mfma_f32_16x16x4_f32 v[100:103], v50, v54, v[100:103]
	ds_read_b32 v49, v68 offset:144
	ds_read_b32 v45, v67 offset:17664
	ds_read_b32 v46, v67 offset:17728
	ds_read_b32 v47, v67 offset:17792
	ds_read_b32 v48, v67 offset:17856
	v_mfma_f32_16x16x4_f32 v[104:107], v51, v54, v[104:107]
	v_mfma_f32_16x16x4_f32 v[108:111], v52, v54, v[108:111]
	v_mfma_f32_16x16x4_f32 v[112:115], v53, v54, v[112:115]
	s_waitcnt lgkmcnt(5)
	v_mfma_f32_16x16x4_f32 v[100:103], v55, v59, v[100:103]
	ds_read_b32 v54, v68 offset:160
	ds_read_b32 v50, v67 offset:18688
	ds_read_b32 v51, v67 offset:18752
	ds_read_b32 v52, v67 offset:18816
	ds_read_b32 v53, v67 offset:18880
	v_mfma_f32_16x16x4_f32 v[104:107], v56, v59, v[104:107]
	v_mfma_f32_16x16x4_f32 v[108:111], v57, v59, v[108:111]
	v_mfma_f32_16x16x4_f32 v[112:115], v58, v59, v[112:115]
	s_waitcnt lgkmcnt(5)
	v_mfma_f32_16x16x4_f32 v[100:103], v45, v49, v[100:103]
	ds_read_b32 v59, v68 offset:176
	ds_read_b32 v55, v67 offset:19712
	ds_read_b32 v56, v67 offset:19776
	ds_read_b32 v57, v67 offset:19840
	ds_read_b32 v58, v67 offset:19904
	v_mfma_f32_16x16x4_f32 v[104:107], v46, v49, v[104:107]
	v_mfma_f32_16x16x4_f32 v[108:111], v47, v49, v[108:111]
	v_mfma_f32_16x16x4_f32 v[112:115], v48, v49, v[112:115]
	s_waitcnt lgkmcnt(5)
	v_mfma_f32_16x16x4_f32 v[100:103], v50, v54, v[100:103]
	ds_read_b32 v49, v68 offset:192
	ds_read_b32 v45, v67 offset:20736
	ds_read_b32 v46, v67 offset:20800
	ds_read_b32 v47, v67 offset:20864
	ds_read_b32 v48, v67 offset:20928
	v_mfma_f32_16x16x4_f32 v[104:107], v51, v54, v[104:107]
	v_mfma_f32_16x16x4_f32 v[108:111], v52, v54, v[108:111]
	v_mfma_f32_16x16x4_f32 v[112:115], v53, v54, v[112:115]
	s_waitcnt lgkmcnt(5)
	v_mfma_f32_16x16x4_f32 v[100:103], v55, v59, v[100:103]
	ds_read_b32 v54, v68 offset:208
	ds_read_b32 v50, v67 offset:21760
	ds_read_b32 v51, v67 offset:21824
	ds_read_b32 v52, v67 offset:21888
	ds_read_b32 v53, v67 offset:21952
	v_mfma_f32_16x16x4_f32 v[104:107], v56, v59, v[104:107]
	v_mfma_f32_16x16x4_f32 v[108:111], v57, v59, v[108:111]
	v_mfma_f32_16x16x4_f32 v[112:115], v58, v59, v[112:115]
	s_waitcnt lgkmcnt(5)
	v_mfma_f32_16x16x4_f32 v[100:103], v45, v49, v[100:103]
	ds_read_b32 v59, v68 offset:224
	ds_read_b32 v55, v67 offset:22784
	ds_read_b32 v56, v67 offset:22848
	ds_read_b32 v57, v67 offset:22912
	ds_read_b32 v58, v67 offset:22976
	v_mfma_f32_16x16x4_f32 v[104:107], v46, v49, v[104:107]
	v_mfma_f32_16x16x4_f32 v[108:111], v47, v49, v[108:111]
	v_mfma_f32_16x16x4_f32 v[112:115], v48, v49, v[112:115]
	s_waitcnt lgkmcnt(5)
	v_mfma_f32_16x16x4_f32 v[100:103], v50, v54, v[100:103]
	ds_read_b32 v49, v68 offset:240
	ds_read_b32 v45, v67 offset:23808
	ds_read_b32 v46, v67 offset:23872
	ds_read_b32 v47, v67 offset:23936
	ds_read_b32 v48, v67 offset:24000
	v_mfma_f32_16x16x4_f32 v[104:107], v51, v54, v[104:107]
	v_mfma_f32_16x16x4_f32 v[108:111], v52, v54, v[108:111]
	v_mfma_f32_16x16x4_f32 v[112:115], v53, v54, v[112:115]
	s_waitcnt lgkmcnt(5)
	v_mfma_f32_16x16x4_f32 v[100:103], v55, v59, v[100:103]
	v_mfma_f32_16x16x4_f32 v[104:107], v56, v59, v[104:107]
	v_mfma_f32_16x16x4_f32 v[108:111], v57, v59, v[108:111]
	v_mfma_f32_16x16x4_f32 v[112:115], v58, v59, v[112:115]
	s_waitcnt lgkmcnt(0)
	v_mfma_f32_16x16x4_f32 v[100:103], v45, v49, v[100:103]
	v_mfma_f32_16x16x4_f32 v[104:107], v46, v49, v[104:107]
	v_mfma_f32_16x16x4_f32 v[108:111], v47, v49, v[108:111]
	v_mfma_f32_16x16x4_f32 v[112:115], v48, v49, v[112:115]
	s_nop 7
	s_nop 3
	v_mul_f32_e32 v100, v20, v100
	v_mul_f32_e32 v101, v21, v101
	v_mul_f32_e32 v102, v22, v102
	v_mul_f32_e32 v103, v23, v103
	v_mul_f32_e32 v104, v24, v104
	v_mul_f32_e32 v105, v25, v105
	v_mul_f32_e32 v106, v26, v106
	v_mul_f32_e32 v107, v27, v107
	v_mul_f32_e32 v108, v28, v108
	v_mul_f32_e32 v109, v29, v109
	v_mul_f32_e32 v110, v30, v110
	v_mul_f32_e32 v111, v31, v111
	v_mul_f32_e32 v112, v32, v112
	v_mul_f32_e32 v113, v33, v113
	v_mul_f32_e32 v114, v34, v114
	v_mul_f32_e32 v115, v35, v115
	v_sin_f32_e32 v100, v100
	v_sin_f32_e32 v101, v101
	v_sin_f32_e32 v102, v102
	v_sin_f32_e32 v103, v103
	v_sin_f32_e32 v104, v104
	v_sin_f32_e32 v105, v105
	v_sin_f32_e32 v106, v106
	v_sin_f32_e32 v107, v107
	v_sin_f32_e32 v108, v108
	v_sin_f32_e32 v109, v109
	v_sin_f32_e32 v110, v110
	v_sin_f32_e32 v111, v111
	v_sin_f32_e32 v112, v112
	v_sin_f32_e32 v113, v113
	v_sin_f32_e32 v114, v114
	v_sin_f32_e32 v115, v115
	s_nop 1
	ds_write_b128 v69, v[100:103] offset:0
	ds_write_b128 v69, v[104:107] offset:64
	ds_write_b128 v69, v[108:111] offset:128
	ds_write_b128 v69, v[112:115] offset:192
	s_waitcnt lgkmcnt(0)
	ds_read_b128 v[4:7], v70 offset:41728
	ds_read_b128 v[8:11], v70 offset:41792
	ds_read_b128 v[12:15], v70 offset:41856
	ds_read_b128 v[16:19], v70 offset:41920
	ds_read_b32 v49, v68 offset:0
	ds_read_b32 v45, v67 offset:24832
	ds_read_b32 v46, v67 offset:24896
	ds_read_b32 v47, v67 offset:24960
	ds_read_b32 v48, v67 offset:25024
	ds_read_b32 v54, v68 offset:16
	ds_read_b32 v50, v67 offset:25856
	ds_read_b32 v51, v67 offset:25920
	ds_read_b32 v52, v67 offset:25984
	ds_read_b32 v53, v67 offset:26048
	s_waitcnt lgkmcnt(5)
	v_mfma_f32_16x16x4_f32 v[4:7], v45, v49, v[4:7]
	ds_read_b32 v59, v68 offset:32
	ds_read_b32 v55, v67 offset:26880
	ds_read_b32 v56, v67 offset:26944
	ds_read_b32 v57, v67 offset:27008
	ds_read_b32 v58, v67 offset:27072
	v_mfma_f32_16x16x4_f32 v[8:11], v46, v49, v[8:11]
	v_mfma_f32_16x16x4_f32 v[12:15], v47, v49, v[12:15]
	v_mfma_f32_16x16x4_f32 v[16:19], v48, v49, v[16:19]
	s_waitcnt lgkmcnt(5)
	v_mfma_f32_16x16x4_f32 v[4:7], v50, v54, v[4:7]
	ds_read_b32 v49, v68 offset:48
	ds_read_b32 v45, v67 offset:27904
	ds_read_b32 v46, v67 offset:27968
	ds_read_b32 v47, v67 offset:28032
	ds_read_b32 v48, v67 offset:28096
	v_mfma_f32_16x16x4_f32 v[8:11], v51, v54, v[8:11]
	v_mfma_f32_16x16x4_f32 v[12:15], v52, v54, v[12:15]
	v_mfma_f32_16x16x4_f32 v[16:19], v53, v54, v[16:19]
	s_waitcnt lgkmcnt(5)
	v_mfma_f32_16x16x4_f32 v[4:7], v55, v59, v[4:7]
	ds_read_b32 v54, v68 offset:64
	ds_read_b32 v50, v67 offset:28928
	ds_read_b32 v51, v67 offset:28992
	ds_read_b32 v52, v67 offset:29056
	ds_read_b32 v53, v67 offset:29120
	v_mfma_f32_16x16x4_f32 v[8:11], v56, v59, v[8:11]
	v_mfma_f32_16x16x4_f32 v[12:15], v57, v59, v[12:15]
	v_mfma_f32_16x16x4_f32 v[16:19], v58, v59, v[16:19]
	s_waitcnt lgkmcnt(5)
	v_mfma_f32_16x16x4_f32 v[4:7], v45, v49, v[4:7]
	ds_read_b32 v59, v68 offset:80
	ds_read_b32 v55, v67 offset:29952
	ds_read_b32 v56, v67 offset:30016
	ds_read_b32 v57, v67 offset:30080
	ds_read_b32 v58, v67 offset:30144
	v_mfma_f32_16x16x4_f32 v[8:11], v46, v49, v[8:11]
	v_mfma_f32_16x16x4_f32 v[12:15], v47, v49, v[12:15]
	v_mfma_f32_16x16x4_f32 v[16:19], v48, v49, v[16:19]
	s_waitcnt lgkmcnt(5)
	v_mfma_f32_16x16x4_f32 v[4:7], v50, v54, v[4:7]
	ds_read_b32 v49, v68 offset:96
	ds_read_b32 v45, v67 offset:30976
	ds_read_b32 v46, v67 offset:31040
	ds_read_b32 v47, v67 offset:31104
	ds_read_b32 v48, v67 offset:31168
	v_mfma_f32_16x16x4_f32 v[8:11], v51, v54, v[8:11]
	v_mfma_f32_16x16x4_f32 v[12:15], v52, v54, v[12:15]
	v_mfma_f32_16x16x4_f32 v[16:19], v53, v54, v[16:19]
	s_waitcnt lgkmcnt(5)
	v_mfma_f32_16x16x4_f32 v[4:7], v55, v59, v[4:7]
	ds_read_b32 v54, v68 offset:112
	ds_read_b32 v50, v67 offset:32000
	ds_read_b32 v51, v67 offset:32064
	ds_read_b32 v52, v67 offset:32128
	ds_read_b32 v53, v67 offset:32192
	v_mfma_f32_16x16x4_f32 v[8:11], v56, v59, v[8:11]
	v_mfma_f32_16x16x4_f32 v[12:15], v57, v59, v[12:15]
	v_mfma_f32_16x16x4_f32 v[16:19], v58, v59, v[16:19]
	s_waitcnt lgkmcnt(5)
	v_mfma_f32_16x16x4_f32 v[4:7], v45, v49, v[4:7]
	ds_read_b32 v59, v68 offset:128
	ds_read_b32 v55, v67 offset:33024
	ds_read_b32 v56, v67 offset:33088
	ds_read_b32 v57, v67 offset:33152
	ds_read_b32 v58, v67 offset:33216
	v_mfma_f32_16x16x4_f32 v[8:11], v46, v49, v[8:11]
	v_mfma_f32_16x16x4_f32 v[12:15], v47, v49, v[12:15]
	v_mfma_f32_16x16x4_f32 v[16:19], v48, v49, v[16:19]
	s_waitcnt lgkmcnt(5)
	v_mfma_f32_16x16x4_f32 v[4:7], v50, v54, v[4:7]
	ds_read_b32 v49, v68 offset:144
	ds_read_b32 v45, v67 offset:34048
	ds_read_b32 v46, v67 offset:34112
	ds_read_b32 v47, v67 offset:34176
	ds_read_b32 v48, v67 offset:34240
	v_mfma_f32_16x16x4_f32 v[8:11], v51, v54, v[8:11]
	v_mfma_f32_16x16x4_f32 v[12:15], v52, v54, v[12:15]
	v_mfma_f32_16x16x4_f32 v[16:19], v53, v54, v[16:19]
	s_waitcnt lgkmcnt(5)
	v_mfma_f32_16x16x4_f32 v[4:7], v55, v59, v[4:7]
	ds_read_b32 v54, v68 offset:160
	ds_read_b32 v50, v67 offset:35072
	ds_read_b32 v51, v67 offset:35136
	ds_read_b32 v52, v67 offset:35200
	ds_read_b32 v53, v67 offset:35264
	v_mfma_f32_16x16x4_f32 v[8:11], v56, v59, v[8:11]
	v_mfma_f32_16x16x4_f32 v[12:15], v57, v59, v[12:15]
	v_mfma_f32_16x16x4_f32 v[16:19], v58, v59, v[16:19]
	s_waitcnt lgkmcnt(5)
	v_mfma_f32_16x16x4_f32 v[4:7], v45, v49, v[4:7]
	ds_read_b32 v59, v68 offset:176
	ds_read_b32 v55, v67 offset:36096
	ds_read_b32 v56, v67 offset:36160
	ds_read_b32 v57, v67 offset:36224
	ds_read_b32 v58, v67 offset:36288
	v_mfma_f32_16x16x4_f32 v[8:11], v46, v49, v[8:11]
	v_mfma_f32_16x16x4_f32 v[12:15], v47, v49, v[12:15]
	v_mfma_f32_16x16x4_f32 v[16:19], v48, v49, v[16:19]
	s_waitcnt lgkmcnt(5)
	v_mfma_f32_16x16x4_f32 v[4:7], v50, v54, v[4:7]
	ds_read_b32 v49, v68 offset:192
	ds_read_b32 v45, v67 offset:37120
	ds_read_b32 v46, v67 offset:37184
	ds_read_b32 v47, v67 offset:37248
	ds_read_b32 v48, v67 offset:37312
	v_mfma_f32_16x16x4_f32 v[8:11], v51, v54, v[8:11]
	v_mfma_f32_16x16x4_f32 v[12:15], v52, v54, v[12:15]
	v_mfma_f32_16x16x4_f32 v[16:19], v53, v54, v[16:19]
	s_waitcnt lgkmcnt(5)
	v_mfma_f32_16x16x4_f32 v[4:7], v55, v59, v[4:7]
	ds_read_b32 v54, v68 offset:208
	ds_read_b32 v50, v67 offset:38144
	ds_read_b32 v51, v67 offset:38208
	ds_read_b32 v52, v67 offset:38272
	ds_read_b32 v53, v67 offset:38336
	v_mfma_f32_16x16x4_f32 v[8:11], v56, v59, v[8:11]
	v_mfma_f32_16x16x4_f32 v[12:15], v57, v59, v[12:15]
	v_mfma_f32_16x16x4_f32 v[16:19], v58, v59, v[16:19]
	s_waitcnt lgkmcnt(5)
	v_mfma_f32_16x16x4_f32 v[4:7], v45, v49, v[4:7]
	ds_read_b32 v59, v68 offset:224
	ds_read_b32 v55, v67 offset:39168
	ds_read_b32 v56, v67 offset:39232
	ds_read_b32 v57, v67 offset:39296
	ds_read_b32 v58, v67 offset:39360
	v_mfma_f32_16x16x4_f32 v[8:11], v46, v49, v[8:11]
	v_mfma_f32_16x16x4_f32 v[12:15], v47, v49, v[12:15]
	v_mfma_f32_16x16x4_f32 v[16:19], v48, v49, v[16:19]
	s_waitcnt lgkmcnt(5)
	v_mfma_f32_16x16x4_f32 v[4:7], v50, v54, v[4:7]
	ds_read_b32 v49, v68 offset:240
	ds_read_b32 v45, v67 offset:40192
	ds_read_b32 v46, v67 offset:40256
	ds_read_b32 v47, v67 offset:40320
	ds_read_b32 v48, v67 offset:40384
	v_mfma_f32_16x16x4_f32 v[8:11], v51, v54, v[8:11]
	v_mfma_f32_16x16x4_f32 v[12:15], v52, v54, v[12:15]
	v_mfma_f32_16x16x4_f32 v[16:19], v53, v54, v[16:19]
	s_waitcnt lgkmcnt(5)
	v_mfma_f32_16x16x4_f32 v[4:7], v55, v59, v[4:7]
	v_mfma_f32_16x16x4_f32 v[8:11], v56, v59, v[8:11]
	v_mfma_f32_16x16x4_f32 v[12:15], v57, v59, v[12:15]
	v_mfma_f32_16x16x4_f32 v[16:19], v58, v59, v[16:19]
	s_waitcnt lgkmcnt(0)
	v_mfma_f32_16x16x4_f32 v[4:7], v45, v49, v[4:7]
	v_mfma_f32_16x16x4_f32 v[8:11], v46, v49, v[8:11]
	v_mfma_f32_16x16x4_f32 v[12:15], v47, v49, v[12:15]
	v_mfma_f32_16x16x4_f32 v[16:19], v48, v49, v[16:19]
	s_nop 7
	s_nop 3
	v_mul_f32_e32 v4, v20, v4
	v_mul_f32_e32 v5, v21, v5
	v_mul_f32_e32 v6, v22, v6
	v_mul_f32_e32 v7, v23, v7
	v_mul_f32_e32 v8, v24, v8
	v_mul_f32_e32 v9, v25, v9
	v_mul_f32_e32 v10, v26, v10
	v_mul_f32_e32 v11, v27, v11
	v_mul_f32_e32 v12, v28, v12
	v_mul_f32_e32 v13, v29, v13
	v_mul_f32_e32 v14, v30, v14
	v_mul_f32_e32 v15, v31, v15
	v_mul_f32_e32 v16, v32, v16
	v_mul_f32_e32 v17, v33, v17
	v_mul_f32_e32 v18, v34, v18
	v_mul_f32_e32 v19, v35, v19
	v_sin_f32_e32 v4, v4
	v_sin_f32_e32 v5, v5
	v_sin_f32_e32 v6, v6
	v_sin_f32_e32 v7, v7
	v_sin_f32_e32 v8, v8
	v_sin_f32_e32 v9, v9
	v_sin_f32_e32 v10, v10
	v_sin_f32_e32 v11, v11
	v_sin_f32_e32 v12, v12
	v_sin_f32_e32 v13, v13
	v_sin_f32_e32 v14, v14
	v_sin_f32_e32 v15, v15
	v_sin_f32_e32 v16, v16
	v_sin_f32_e32 v17, v17
	v_sin_f32_e32 v18, v18
	v_sin_f32_e32 v19, v19
	s_nop 1
	v_bfe_u32 v76, v4, 16, 1
	v_bfe_u32 v77, v5, 16, 1
	v_bfe_u32 v78, v6, 16, 1
	v_bfe_u32 v79, v7, 16, 1
	v_add3_u32 v4, v4, v76, s30
	v_add3_u32 v5, v5, v77, s30
	v_add3_u32 v6, v6, v78, s30
	v_add3_u32 v7, v7, v79, s30
	v_perm_b32 v4, v5, v4, s31
	v_perm_b32 v5, v7, v6, s31
	global_store_dwordx2 v92, v[4:5], s[26:27] offset:0
	v_bfe_u32 v76, v8, 16, 1
	v_bfe_u32 v77, v9, 16, 1
	v_bfe_u32 v78, v10, 16, 1
	v_bfe_u32 v79, v11, 16, 1
	v_add3_u32 v8, v8, v76, s30
	v_add3_u32 v9, v9, v77, s30
	v_add3_u32 v10, v10, v78, s30
	v_add3_u32 v11, v11, v79, s30
	v_perm_b32 v8, v9, v8, s31
	v_perm_b32 v9, v11, v10, s31
	global_store_dwordx2 v92, v[8:9], s[26:27] offset:32
	v_bfe_u32 v76, v12, 16, 1
	v_bfe_u32 v77, v13, 16, 1
	v_bfe_u32 v78, v14, 16, 1
	v_bfe_u32 v79, v15, 16, 1
	v_add3_u32 v12, v12, v76, s30
	v_add3_u32 v13, v13, v77, s30
	v_add3_u32 v14, v14, v78, s30
	v_add3_u32 v15, v15, v79, s30
	v_perm_b32 v12, v13, v12, s31
	v_perm_b32 v13, v15, v14, s31
	global_store_dwordx2 v92, v[12:13], s[26:27] offset:64
	v_bfe_u32 v76, v16, 16, 1
	v_bfe_u32 v77, v17, 16, 1
	v_bfe_u32 v78, v18, 16, 1
	v_bfe_u32 v79, v19, 16, 1
	v_add3_u32 v16, v16, v76, s30
	v_add3_u32 v17, v17, v77, s30
	v_add3_u32 v18, v18, v78, s30
	v_add3_u32 v19, v19, v79, s30
	v_perm_b32 v16, v17, v16, s31
	v_perm_b32 v17, v19, v18, s31
	global_store_dwordx2 v92, v[16:17], s[26:27] offset:96
	s_branch .Lmy_padb
	s_nop 0
	s_nop 0
	s_nop 0
	s_nop 0
	s_nop 0
	s_nop 0
	s_nop 0
	s_nop 0
	s_nop 0
	s_nop 0
	s_nop 0
	s_nop 0
	s_nop 0
	s_nop 0
.Lmy_padb:
.LBB0_39:
	s_or_b64 exec, exec, s[8:9]
	s_movk_i32 s0, 0x1040
	v_cmp_gt_i32_e32 vcc, s0, v66
	s_barrier
	s_and_saveexec_b64 s[4:5], vcc
	s_cbranch_execz .LBB0_129
	s_movk_i32 s0, 0x4100
	v_mad_u32_u24 v3, v200, s0, 0
	v_lshrrev_b32_e32 v1, 4, v64
	s_movk_i32 s0, 0x104
	v_mov_b32_e32 v5, 0x410
	s_add_u32 s8, s56, 0x1c000000
	v_mad_u32_u24 v67, v1, s0, v5
	v_mov_b32_e32 v5, 0x820
	s_addc_u32 s9, s57, 0
	v_mad_u32_u24 v74, v1, s0, v5
	v_mov_b32_e32 v5, 0xc30
	s_add_u32 s24, s56, 0x1dc00000
	v_mad_u32_u24 v76, v1, s0, v5
	v_mov_b32_e32 v5, 0x1040
	s_addc_u32 s25, s57, 0
	v_mad_u32_u24 v78, v1, s0, v5
	v_mov_b32_e32 v5, 0x1450
	s_add_u32 s26, s56, 0x1e720000
	v_mad_u32_u24 v80, v1, s0, v5
	v_mov_b32_e32 v5, 0x1860
	v_readlane_b32 s36, v244, 0
	s_addc_u32 s27, s57, 0
	v_mad_u32_u24 v82, v1, s0, v5
	v_mov_b32_e32 v5, 0x1c70
	s_lshl_b32 s29, s29, 3
	v_readlane_b32 s40, v244, 4
	v_mad_u32_u24 v84, v1, s0, v5
	v_mov_b32_e32 v5, 0x2080
	v_readlane_b32 s41, v244, 5
	s_add_u32 s30, s40, 0xfffff000
	v_mad_u32_u24 v86, v1, s0, v5
	v_mov_b32_e32 v5, 0x2490
	s_addc_u32 s31, s41, -1
	v_and_b32_e32 v2, 60, v2
	v_mad_u32_u24 v88, v1, s0, v5
	v_mov_b32_e32 v5, 0x28a0
	v_readlane_b32 s37, v244, 1
	s_cmp_lg_u64 s[16:17], 0
	v_lshlrev_b32_e32 v14, 2, v2
	v_or_b32_e32 v65, 4, v1
	v_or_b32_e32 v73, 8, v1
	v_or_b32_e32 v75, 12, v1
	v_or_b32_e32 v77, 16, v1
	v_or_b32_e32 v79, 20, v1
	v_or_b32_e32 v81, 24, v1
	v_or_b32_e32 v83, 28, v1
	v_or_b32_e32 v85, 32, v1
	v_or_b32_e32 v87, 36, v1
	v_or_b32_e32 v89, 40, v1
	v_mad_u32_u24 v90, v1, s0, v5
	v_or_b32_e32 v91, 44, v1
	v_or_b32_e32 v92, 48, v1
	v_or_b32_e32 v93, 52, v1
	v_or_b32_e32 v94, 56, v1
	v_or_b32_e32 v95, 60, v1
	s_cselect_b64 s[36:37], -1, 0
	s_lshl_b32 s0, s28, 9
	s_lshl_b32 s1, s34, 9
	v_add_u32_e32 v57, v3, v14
	v_lshlrev_b32_e32 v2, 12, v1
	v_mov_b32_e32 v15, 0
	v_lshlrev_b32_e32 v4, 12, v65
	v_lshlrev_b32_e32 v6, 12, v73
	v_lshlrev_b32_e32 v8, 12, v75
	v_lshlrev_b32_e32 v10, 12, v77
	v_lshlrev_b32_e32 v12, 12, v79
	v_lshlrev_b32_e32 v36, 12, v81
	v_lshlrev_b32_e32 v38, 12, v83
	v_lshlrev_b32_e32 v40, 12, v85
	v_lshlrev_b32_e32 v42, 12, v87
	v_lshlrev_b32_e32 v44, 12, v89
	v_lshlrev_b32_e32 v46, 12, v91
	v_lshlrev_b32_e32 v48, 12, v92
	v_lshlrev_b32_e32 v50, 12, v93
	v_lshlrev_b32_e32 v52, 12, v94
	v_lshlrev_b32_e32 v54, 12, v95
	v_lshl_add_u32 v96, v64, 2, v3
	v_readlane_b32 s42, v244, 6
	v_readlane_b32 s43, v244, 7
	v_mov_b32_e32 v3, 0xfffc0000
	s_sub_i32 s33, s0, s1
	s_lshl_b32 s0, s28, 4
	s_lshl_b32 s1, s34, 4
	v_mul_u32_u24_e32 v63, 0x104, v1
	v_lshl_add_u64 v[16:17], s[44:45], 0, v[14:15]
	v_lshl_add_u64 v[18:19], s[42:43], 0, v[14:15]
	v_lshl_add_u64 v[20:21], s[18:19], 0, v[14:15]
	s_mov_b64 s[18:19], 0
	v_lshl_add_u32 v22, v66, 6, v3
	v_lshlrev_b32_e32 v97, 1, v66
	s_sub_i32 s34, s0, s1
	s_movk_i32 s35, 0xbff
	s_movk_i32 s44, 0xfff
	v_lshlrev_b32_e32 v24, 2, v2
	v_lshlrev_b32_e32 v26, 2, v4
	v_lshlrev_b32_e32 v28, 2, v6
	v_lshlrev_b32_e32 v30, 2, v8
	v_lshlrev_b32_e32 v32, 2, v10
	v_lshlrev_b32_e32 v34, 2, v12
	v_lshlrev_b32_e32 v36, 2, v36
	v_lshlrev_b32_e32 v38, 2, v38
	v_lshlrev_b32_e32 v40, 2, v40
	v_lshlrev_b32_e32 v42, 2, v42
	v_lshlrev_b32_e32 v44, 2, v44
	v_lshlrev_b32_e32 v46, 2, v46
	v_lshlrev_b32_e32 v48, 2, v48
	v_lshlrev_b32_e32 v50, 2, v50
	v_lshlrev_b32_e32 v52, 2, v52
	v_lshlrev_b32_e32 v54, 2, v54
	s_movk_i32 s45, 0x7fff
	s_mov_b32 s46, 0xffff0000
	s_movk_i32 s47, 0x13ff
	s_movk_i32 s60, 0x103f
	v_readlane_b32 s38, v244, 2
	v_readlane_b32 s39, v244, 3
	s_branch .LBB0_44
